# grid barrier: poll more often (s_sleep 6 to 1) and XCD leader releases followers before invalidating its own L1
# baseline (speedup 1.0000x reference)
.LBB0_98:
	s_and_b32 s24, s26, 0xff
	s_mov_b64 s[22:23], -1
	s_cmp_lg_u32 s24, 0
	s_mov_b64 s[58:59], -1
	s_sleep 1
	s_cbranch_scc0 .LBB0_101
	s_and_b64 vcc, exec, s[58:59]
	s_cbranch_vccz .LBB0_97

.LBB0_115:
	s_and_b32 s22, s26, 0xff
	s_cmp_lg_u32 s22, 0
	s_mov_b64 s[24:25], -1
	s_sleep 1
	s_cbranch_scc0 .LBB0_118
	s_mov_b64 s[58:59], -1
	s_and_b64 vcc, exec, s[24:25]
	s_cbranch_vccz .LBB0_114

.LBB0_125:
	s_or_b64 exec, exec, s[6:7]
	s_mov_b64 s[6:7], exec
	v_mbcnt_lo_u32_b32 v0, s6, 0
	v_mbcnt_hi_u32_b32 v0, s7, v0
	v_cmp_eq_u32_e32 vcc, 0, v0
	s_waitcnt vmcnt(0)
	s_and_saveexec_b64 s[8:9], vcc
	s_cbranch_execz .LBB0_127
	s_bcnt1_i32_b64 s6, s[6:7]
	v_mov_b32_e32 v0, 0x2000
	v_mov_b32_e32 v1, s6
	global_atomic_add v0, v1, s[4:5] offset:1024
.LBB0_127:
	s_or_b64 exec, exec, s[8:9]
	buffer_inv sc1
	s_waitcnt vmcnt(0)

.LBB0_162:
	s_and_b32 s24, s26, 0xff
	s_mov_b64 s[22:23], -1
	s_cmp_lg_u32 s24, 0
	s_mov_b64 s[72:73], -1
	s_sleep 1
	s_cbranch_scc0 .LBB0_165
	s_and_b64 vcc, exec, s[72:73]
	s_cbranch_vccz .LBB0_161

.LBB0_179:
	s_and_b32 s22, s26, 0xff
	s_cmp_lg_u32 s22, 0
	s_mov_b64 s[24:25], -1
	s_sleep 1
	s_cbranch_scc0 .LBB0_182
	s_mov_b64 s[72:73], -1
	s_and_b64 vcc, exec, s[24:25]
	s_cbranch_vccz .LBB0_178

.LBB0_289:
	s_and_b32 s27, s26, 0xff
	s_mov_b64 s[24:25], -1
	s_cmp_lg_u32 s27, 0
	s_mov_b64 s[40:41], -1
	s_sleep 1
	s_cbranch_scc0 .LBB0_292
	s_and_b64 vcc, exec, s[40:41]
	s_cbranch_vccz .LBB0_288

.LBB0_306:
	s_and_b32 s24, s26, 0xff
	s_cmp_lg_u32 s24, 0
	s_mov_b64 s[38:39], -1
	s_sleep 1
	s_cbranch_scc0 .LBB0_309
	s_mov_b64 s[40:41], -1
	s_and_b64 vcc, exec, s[38:39]
	s_cbranch_vccz .LBB0_305

.LBB0_352:
	s_and_b32 s4, s3, 0xff
	s_mov_b64 s[38:39], -1
	s_cmp_lg_u32 s4, 0
	s_mov_b64 s[42:43], -1
	s_sleep 1
	s_cbranch_scc0 .LBB0_355
	s_and_b64 vcc, exec, s[42:43]
	s_cbranch_vccz .LBB0_351

.LBB0_369:
	s_and_b32 s4, s3, 0xff
	s_cmp_lg_u32 s4, 0
	s_mov_b64 s[40:41], -1
	s_sleep 1
	s_cbranch_scc0 .LBB0_372
	s_mov_b64 s[42:43], -1
	s_and_b64 vcc, exec, s[40:41]
	s_cbranch_vccz .LBB0_368

.LBB0_379:
	s_or_b64 exec, exec, s[8:9]
	s_mov_b64 s[8:9], exec
	v_mbcnt_lo_u32_b32 v0, s8, 0
	v_mbcnt_hi_u32_b32 v0, s9, v0
	v_cmp_eq_u32_e32 vcc, 0, v0
	s_waitcnt vmcnt(0)
	s_and_saveexec_b64 s[16:17], vcc
	s_cbranch_execz .LBB0_381
	s_bcnt1_i32_b64 s3, s[8:9]
	v_mov_b32_e32 v0, 0x2000
	v_mov_b32_e32 v1, s3
	global_atomic_add v0, v1, s[6:7] offset:1024
.LBB0_381:
	s_or_b64 exec, exec, s[16:17]
	buffer_inv sc1
	s_waitcnt vmcnt(0)

.LBB0_537:
	s_and_b32 s4, s3, 0xff
	s_mov_b64 s[48:49], -1
	s_cmp_lg_u32 s4, 0
	s_mov_b64 s[52:53], -1
	s_sleep 1
	s_cbranch_scc0 .LBB0_540
	s_and_b64 vcc, exec, s[52:53]
	s_cbranch_vccz .LBB0_536

.LBB0_554:
	s_and_b32 s4, s3, 0xff
	s_cmp_lg_u32 s4, 0
	s_mov_b64 s[50:51], -1
	s_sleep 1
	s_cbranch_scc0 .LBB0_557
	s_mov_b64 s[52:53], -1
	s_and_b64 vcc, exec, s[50:51]
	s_cbranch_vccz .LBB0_553

.LBB0_564:
	s_or_b64 exec, exec, s[8:9]
	s_mov_b64 s[8:9], exec
	v_mbcnt_lo_u32_b32 v0, s8, 0
	v_mbcnt_hi_u32_b32 v0, s9, v0
	v_cmp_eq_u32_e32 vcc, 0, v0
	s_waitcnt vmcnt(0)
	s_and_saveexec_b64 s[12:13], vcc
	s_cbranch_execz .LBB0_566
	s_bcnt1_i32_b64 s3, s[8:9]
	v_mov_b32_e32 v0, 0x2000
	v_mov_b32_e32 v1, s3
	global_atomic_add v0, v1, s[6:7] offset:1024
.LBB0_566:
	s_or_b64 exec, exec, s[12:13]
	buffer_inv sc1
	s_waitcnt vmcnt(0)

.LBB0_624:
	s_and_b32 s4, s3, 0xff
	s_mov_b64 s[22:23], -1
	s_cmp_lg_u32 s4, 0
	s_mov_b64 s[50:51], -1
	s_sleep 1
	s_cbranch_scc0 .LBB0_627
	s_and_b64 vcc, exec, s[50:51]
	s_cbranch_vccz .LBB0_623

.LBB0_641:
	s_and_b32 s4, s3, 0xff
	s_cmp_lg_u32 s4, 0
	s_mov_b64 s[24:25], -1
	s_sleep 1
	s_cbranch_scc0 .LBB0_644
	s_mov_b64 s[50:51], -1
	s_and_b64 vcc, exec, s[24:25]
	s_cbranch_vccz .LBB0_640

.LBB0_651:
	s_or_b64 exec, exec, s[8:9]
	s_mov_b64 s[8:9], exec
	v_mbcnt_lo_u32_b32 v0, s8, 0
	v_mbcnt_hi_u32_b32 v0, s9, v0
	v_cmp_eq_u32_e32 vcc, 0, v0
	s_waitcnt vmcnt(0)
	s_and_saveexec_b64 s[10:11], vcc
	s_cbranch_execz .LBB0_653
	s_bcnt1_i32_b64 s3, s[8:9]
	v_mov_b32_e32 v0, 0x2000
	v_mov_b32_e32 v1, s3
	global_atomic_add v0, v1, s[6:7] offset:1024
.LBB0_653:
	s_or_b64 exec, exec, s[10:11]
	buffer_inv sc1
	s_waitcnt vmcnt(0)

.LBB0_785:
	s_and_b32 s4, s3, 0xff
	s_mov_b64 s[22:23], -1
	s_cmp_lg_u32 s4, 0
	s_mov_b64 s[44:45], -1
	s_sleep 1
	s_cbranch_scc0 .LBB0_788
	s_and_b64 vcc, exec, s[44:45]
	s_cbranch_vccz .LBB0_784

.LBB0_802:
	s_and_b32 s4, s3, 0xff
	s_cmp_lg_u32 s4, 0
	s_mov_b64 s[24:25], -1
	s_sleep 1
	s_cbranch_scc0 .LBB0_805
	s_mov_b64 s[44:45], -1
	s_and_b64 vcc, exec, s[24:25]
	s_cbranch_vccz .LBB0_801

.LBB0_812:
	s_or_b64 exec, exec, s[10:11]
	s_mov_b64 s[10:11], exec
	v_mbcnt_lo_u32_b32 v0, s10, 0
	v_mbcnt_hi_u32_b32 v0, s11, v0
	v_cmp_eq_u32_e32 vcc, 0, v0
	s_waitcnt vmcnt(0)
	s_and_saveexec_b64 s[12:13], vcc
	s_cbranch_execz .LBB0_814
	s_bcnt1_i32_b64 s3, s[10:11]
	v_mov_b32_e32 v0, 0x2000
	v_mov_b32_e32 v1, s3
	global_atomic_add v0, v1, s[8:9] offset:1024

.LBB0_861:
	s_and_b32 s4, s3, 0xff
	s_mov_b64 s[22:23], -1
	s_cmp_lg_u32 s4, 0
	s_mov_b64 s[42:43], -1
	s_sleep 1
	s_cbranch_scc0 .LBB0_864
	s_and_b64 vcc, exec, s[42:43]
	s_cbranch_vccz .LBB0_860

.LBB0_878:
	s_and_b32 s4, s3, 0xff
	s_cmp_lg_u32 s4, 0
	s_mov_b64 s[24:25], -1
	s_sleep 1
	s_cbranch_scc0 .LBB0_881
	s_mov_b64 s[42:43], -1
	s_and_b64 vcc, exec, s[24:25]
	s_cbranch_vccz .LBB0_877

.LBB0_925:
	s_and_b32 s4, s3, 0xff
	s_mov_b64 s[22:23], -1
	s_cmp_lg_u32 s4, 0
	s_mov_b64 s[38:39], -1
	s_sleep 1
	s_cbranch_scc0 .LBB0_928
	s_and_b64 vcc, exec, s[38:39]
	s_cbranch_vccz .LBB0_924

.LBB0_942:
	s_and_b32 s4, s3, 0xff
	s_cmp_lg_u32 s4, 0
	s_mov_b64 s[24:25], -1
	s_sleep 1
	s_cbranch_scc0 .LBB0_945
	s_mov_b64 s[38:39], -1
	s_and_b64 vcc, exec, s[24:25]
	s_cbranch_vccz .LBB0_941

.LBB0_1178:
	s_and_b32 s5, s4, 0xff
	s_mov_b64 s[18:19], -1
	s_cmp_lg_u32 s5, 0
	s_mov_b64 s[22:23], -1
	s_sleep 1
	s_cbranch_scc0 .LBB0_1181
	s_and_b64 vcc, exec, s[22:23]
	s_cbranch_vccz .LBB0_1177

.LBB0_1195:
	s_and_b32 s5, s4, 0xff
	s_cmp_lg_u32 s5, 0
	s_mov_b64 s[20:21], -1
	s_sleep 1
	s_cbranch_scc0 .LBB0_1198
	s_mov_b64 s[22:23], -1
	s_and_b64 vcc, exec, s[20:21]
	s_cbranch_vccz .LBB0_1194

.LBB0_1205:
	s_or_b64 exec, exec, s[6:7]
	s_mov_b64 s[6:7], exec
	v_mbcnt_lo_u32_b32 v0, s6, 0
	v_mbcnt_hi_u32_b32 v0, s7, v0
	v_cmp_eq_u32_e32 vcc, 0, v0
	s_waitcnt vmcnt(0)
	s_and_saveexec_b64 s[8:9], vcc
	s_cbranch_execz .LBB0_1207
	s_bcnt1_i32_b64 s4, s[6:7]
	v_mov_b32_e32 v0, 0x2000
	v_mov_b32_e32 v1, s4
	global_atomic_add v0, v1, s[2:3] offset:1024
